# FNet ctx_unit: tile-fill loop and the MFMA loop's 16 matrix-fragment loads de-serialised (loads issued together, counted waits), loop unrolled
# speedup vs baseline: 1.0144x; 1.0144x over previous
; #define GAS __attribute__((address_space(1)))
; #define LAS __attribute__((address_space(3)))
; DI s16x4 vtr(const LAS unsigned char* p) { return __builtin_bit_cast(s16x4, __builtin_amdgcn_ds_read_tr16_b64_v4i16((LAS s16x4*)p)); }
; DI f32x4 mfma16(bf16x8 a, bf16x8 b, f32x4 c) { return __builtin_amdgcn_mfma_f32_16x16x32_bf16(a, b, c, 0, 0, 0); }
; DI void ctx_unit(const Frame& F, const bf16* UC, bf16* Hb, int unit, const bf16* MC  ) {
;     const int kq = unit & 7, u5 = unit >> 3, b = u5 >> 4, g = (u5 >> 2) & 3, mb = u5 & 3;
;     LAS unsigned char* D = F.lds;
;     const bf16* src = UC + (size_t)(NLAT + b * CTXL) * 2048 + g * 512 + mb * 64;
;     for (int p = F.tid; p < 512 * 8; p += 512) { const int row = p >> 3, c8 = p & 7; *(LAS v4u*)(D + row * 144 + c8 * 16) = *(const GAS v4u*)(src + (size_t)(row & 255) * 2048 + (row >> 8) * 256 + c8 * 8); }
;     __syncthreads();
;     const int l15 = F.lane & 15, l4 = F.lane >> 4, q = l15 >> 2, pp = l15 & 3;
;     const bf16* Mq = MC + (size_t)kq * 32 * 512; const float sc = 0.00276213586f  ;
;     { const int t = F.wave, mt = t >> 2, ct = t & 3; f32x4 aA = {0.f, 0.f, 0.f, 0.f}, aB = aA, aBc = aA;
;         const bool z0 = (mb == 0 && ct == 0);
; #pragma unroll 4
;         for (int kk = 0; kk < 8; ++kk) {
;             const LAS unsigned char* ad = D + (kk * 32 + 8 * l4 + q) * 144 + (ct * 16 + 4 * pp) * 2;
;             const s16x4 lo = vtr(ad), hi = vtr(ad + 4 * 144); const bf16x8 af = __builtin_shufflevector(lo, hi, 0, 1, 2, 3, 4, 5, 6, 7);
;             const bf16x8 mcf = ld_frag_g(Mq + (size_t)(mt * 16 + l15) * 512 + kk * 32 + 8 * l4);
;             aA = mfma16(af, mcf, aA);
;             const LAS unsigned char* bd = ad + 256 * 144;
;             const s16x4 lo2 = vtr(bd), hi2 = vtr(bd + 4 * 144); const bf16x8 bf_ = __builtin_shufflevector(lo2, hi2, 0, 1, 2, 3, 4, 5, 6, 7);
;             aB = mfma16(bf_, ld_frag_g(Mq + (size_t)(mt * 16 + l15) * 512 + 256 + kk * 32 + 8 * l4), aB);
;             if (z0) aBc = mfma16(bf_, mcf, aBc); }
.LBB0_341:
	v_ashrrev_i32_e32 v5, 3, v4
	v_lshlrev_b32_e32 v2, 12, v5
	v_and_b32_e32 v2, 0xff000, v2
	v_and_b32_e32 v8, 0xffffff00, v5
	v_lshl_add_u64 v[6:7], s[6:7], 0, v[2:3]
	v_ashrrev_i32_e32 v9, 31, v8
	v_lshl_add_u64 v[6:7], v[8:9], 1, v[6:7]
	v_mov_b32_e32 v31, v3
	v_lshl_add_u64 v[6:7], v[6:7], 0, v[30:31]
	v_mad_u64_u32 v[10:11], s[20:21], v5, s80, v[24:25]
	v_add_co_u32_e32 v112, vcc, 0x40000, v6
	v_addc_co_u32_e32 v113, vcc, 0, v7, vcc
	v_add_co_u32_e32 v114, vcc, 0x80000, v6
	v_addc_co_u32_e32 v115, vcc, 0, v7, vcc
	v_add_co_u32_e32 v116, vcc, 0xc0000, v6
	v_addc_co_u32_e32 v117, vcc, 0, v7, vcc
	global_load_dwordx4 v[48:51], v[6:7], off
	global_load_dwordx4 v[52:55], v[112:113], off
	global_load_dwordx4 v[56:59], v[114:115], off
	global_load_dwordx4 v[60:63], v[116:117], off
	global_load_dwordx4 v[64:67], v[6:7], off offset:512
	global_load_dwordx4 v[68:71], v[112:113], off offset:512
	global_load_dwordx4 v[72:75], v[114:115], off offset:512
	global_load_dwordx4 v[76:79], v[116:117], off offset:512
	s_waitcnt vmcnt(7)
	ds_write_b128 v10, v[48:51]
	s_waitcnt vmcnt(6)
	ds_write_b128 v10, v[52:55] offset:9216
	s_waitcnt vmcnt(5)
	ds_write_b128 v10, v[56:59] offset:18432
	s_waitcnt vmcnt(4)
	ds_write_b128 v10, v[60:63] offset:27648
	s_waitcnt vmcnt(3)
	ds_write_b128 v10, v[64:67] offset:36864
	s_waitcnt vmcnt(2)
	ds_write_b128 v10, v[68:71] offset:46080
	s_waitcnt vmcnt(1)
	ds_write_b128 v10, v[72:75] offset:55296
	s_waitcnt vmcnt(0)
	ds_write_b128 v10, v[76:79] offset:64512
.LBB0_342:
	s_or_b64 exec, exec, s[4:5]
	s_and_b32 s4, s15, 7
	s_lshl_b32 s10, s4, 15
	s_cmp_eq_u32 s19, 0
	v_mov_b32_e32 v4, v3
	v_mov_b32_e32 v5, v3
	s_cselect_b64 s[4:5], -1, 0
	v_mov_b32_e32 v2, v3
	v_mov_b32_e32 v8, 0
	v_mov_b64_e32 v[6:7], v[4:5]
	v_lshl_add_u64 v[32:33], v[28:29], 0, s[10:11]
	s_mov_b32 s6, 0
	s_and_b64 s[4:5], s[4:5], s[78:79]
	v_mov_b64_e32 v[4:5], v[2:3]
	v_mov_b32_e32 v9, v8
	v_mov_b32_e32 v10, v8
	v_mov_b32_e32 v11, v8
	v_mov_b32_e32 v12, v8
	v_mov_b32_e32 v13, v8
	v_mov_b32_e32 v14, v8
	v_mov_b32_e32 v15, v8
	s_waitcnt lgkmcnt(0)
	s_barrier
	global_load_dwordx4 v[48:51], v[32:33], off offset:-704
	global_load_dwordx4 v[52:55], v[32:33], off offset:-192
	global_load_dwordx4 v[56:59], v[32:33], off offset:-640
	global_load_dwordx4 v[60:63], v[32:33], off offset:-128
	global_load_dwordx4 v[64:67], v[32:33], off offset:-576
	global_load_dwordx4 v[68:71], v[32:33], off offset:-64
	global_load_dwordx4 v[72:75], v[32:33], off offset:-512
	global_load_dwordx4 v[76:79], v[32:33], off
	global_load_dwordx4 v[80:83], v[32:33], off offset:-448
	global_load_dwordx4 v[84:87], v[32:33], off offset:64
	global_load_dwordx4 v[88:91], v[32:33], off offset:-384
	global_load_dwordx4 v[92:95], v[32:33], off offset:128
	global_load_dwordx4 v[96:99], v[32:33], off offset:-320
	global_load_dwordx4 v[100:103], v[32:33], off offset:192
	global_load_dwordx4 v[104:107], v[32:33], off offset:-256
	global_load_dwordx4 v[108:111], v[32:33], off offset:256
	s_waitcnt vmcnt(0)
	v_add_u32_e32 v2, s6, v39
	ds_read_b64_tr_b16 v[20:21], v2
	ds_read_b64_tr_b16 v[22:23], v2 offset:576
	v_cndmask_b32_e64 v27, 0, 1, s[4:5]
	v_cmp_ne_u32_e64 s[44:45], 1, v27
	s_andn2_b64 vcc, exec, s[4:5]
	s_waitcnt lgkmcnt(0)
	v_mfma_f32_16x16x32_bf16 v[8:11], v[20:23], v[48:51], v[8:11]
	ds_read_b64_tr_b16 v[20:21], v2 offset:36864
	ds_read_b64_tr_b16 v[22:23], v2 offset:37440
	s_waitcnt lgkmcnt(0)
	v_mfma_f32_16x16x32_bf16 v[12:15], v[20:23], v[52:55], v[12:15]
	s_cbranch_vccnz .Lctx_A_346
	v_mfma_f32_16x16x32_bf16 v[4:7], v[20:23], v[48:51], v[4:7]
.Lctx_A_346:
	ds_read_b64_tr_b16 v[20:21], v2 offset:4608
	ds_read_b64_tr_b16 v[22:23], v2 offset:5184
	s_and_b64 vcc, exec, s[44:45]
	s_waitcnt lgkmcnt(0)
	v_mfma_f32_16x16x32_bf16 v[8:11], v[20:23], v[56:59], v[8:11]
	ds_read_b64_tr_b16 v[20:21], v2 offset:41472
	ds_read_b64_tr_b16 v[22:23], v2 offset:42048
	s_waitcnt lgkmcnt(0)
	v_mfma_f32_16x16x32_bf16 v[12:15], v[20:23], v[60:63], v[12:15]
	s_cbranch_vccnz .Lctx_A_348
	v_mfma_f32_16x16x32_bf16 v[4:7], v[20:23], v[56:59], v[4:7]
; #define GAS __attribute__((address_space(1)))
; #define LAS __attribute__((address_space(3)))
; DI unsigned pk2(float lo, float hi) { f32x2_t v = {lo, hi}; bf16x2_t b = __builtin_convertvector(v, bf16x2_t); return __builtin_bit_cast(unsigned, b); }
; DI s16x4 vtr(const LAS unsigned char* p) { return __builtin_bit_cast(s16x4, __builtin_amdgcn_ds_read_tr16_b64_v4i16((LAS s16x4*)p)); }
; DI f32x4 mfma16(bf16x8 a, bf16x8 b, f32x4 c) { return __builtin_amdgcn_mfma_f32_16x16x32_bf16(a, b, c, 0, 0, 0); }
; DI void ctx_unit(const Frame& F, const bf16* UC, bf16* Hb, int unit, const bf16* MC  ) {
;     ...
;         for (int kk = 0; kk < 8; ++kk) {
;             const LAS unsigned char* ad = D + (kk * 32 + 8 * l4 + q) * 144 + (ct * 16 + 4 * pp) * 2;
;             const s16x4 lo = vtr(ad), hi = vtr(ad + 4 * 144); const bf16x8 af = __builtin_shufflevector(lo, hi, 0, 1, 2, 3, 4, 5, 6, 7);
;             const bf16x8 mcf = ld_frag_g(Mq + (size_t)(mt * 16 + l15) * 512 + kk * 32 + 8 * l4);
;             aA = mfma16(af, mcf, aA);
;             const LAS unsigned char* bd = ad + 256 * 144;
;             const s16x4 lo2 = vtr(bd), hi2 = vtr(bd + 4 * 144); const bf16x8 bf_ = __builtin_shufflevector(lo2, hi2, 0, 1, 2, 3, 4, 5, 6, 7);
;             aB = mfma16(bf_, ld_frag_g(Mq + (size_t)(mt * 16 + l15) * 512 + 256 + kk * 32 + 8 * l4), aB);
;             if (z0) aBc = mfma16(bf_, mcf, aBc); }
;         f32x4 sm = aA + aB; const int kp = kq * 32 + mt * 16 + l15, pos = mb * 64 + ct * 16 + 4 * l4;
;         const bool sp0 = z0 && l4 == 0;
;         if (sp0) sm[0] = aA[0];
;         bf16* o = Hb + (size_t)(NLAT + b * CTXL + kp) * DM + g * 512; v2u p;
;         p.x = pk2(sm[0] * sc, sm[1] * sc); p.y = pk2(sm[2] * sc, sm[3] * sc); *(GAS v2u*)(o + pos) = p;
;         bf16* mo = Hb + (size_t)(NLAT + b * CTXL + ((CTXL - kp) & (CTXL - 1))) * DM + g * 512 + 256 + pos;
;         if (sp0) { *(GAS unsigned short*)(mo + 1) = (unsigned short)(p.x >> 16); *(GAS unsigned*)(mo + 2) = p.y; *(GAS unsigned short*)(o + 256) = (unsigned short)pk2(aBc[0] * sc, 0.f); }
;         else *(GAS v2u*)(mo) = p; }
.Lctx_A_348:
	ds_read_b64_tr_b16 v[20:21], v2 offset:9216
	ds_read_b64_tr_b16 v[22:23], v2 offset:9792
	s_and_b64 vcc, exec, s[44:45]
	s_waitcnt lgkmcnt(0)
	v_mfma_f32_16x16x32_bf16 v[8:11], v[20:23], v[64:67], v[8:11]
	ds_read_b64_tr_b16 v[20:21], v2 offset:46080
	ds_read_b64_tr_b16 v[22:23], v2 offset:46656
	s_waitcnt lgkmcnt(0)
	v_mfma_f32_16x16x32_bf16 v[12:15], v[20:23], v[68:71], v[12:15]
	s_cbranch_vccnz .Lctx_A_350
	v_mfma_f32_16x16x32_bf16 v[4:7], v[20:23], v[64:67], v[4:7]
.Lctx_A_350:
	ds_read_b64_tr_b16 v[20:21], v2 offset:13824
	ds_read_b64_tr_b16 v[22:23], v2 offset:14400
	s_and_b64 vcc, exec, s[44:45]
	s_waitcnt lgkmcnt(0)
	v_mfma_f32_16x16x32_bf16 v[8:11], v[20:23], v[72:75], v[8:11]
	ds_read_b64_tr_b16 v[20:21], v2 offset:50688
	ds_read_b64_tr_b16 v[22:23], v2 offset:51264
	s_waitcnt lgkmcnt(0)
	v_mfma_f32_16x16x32_bf16 v[12:15], v[20:23], v[76:79], v[12:15]
	s_cbranch_vccnz .Lctx_A_end
	v_mfma_f32_16x16x32_bf16 v[4:7], v[20:23], v[72:75], v[4:7]
.Lctx_A_end:
	s_addk_i32 s6, 0x4800
	v_add_u32_e32 v2, s6, v39
	ds_read_b64_tr_b16 v[20:21], v2
	ds_read_b64_tr_b16 v[22:23], v2 offset:576
	v_cndmask_b32_e64 v27, 0, 1, s[4:5]
	v_cmp_ne_u32_e64 s[44:45], 1, v27
	s_andn2_b64 vcc, exec, s[4:5]
	s_waitcnt lgkmcnt(0)
	v_mfma_f32_16x16x32_bf16 v[8:11], v[20:23], v[80:83], v[8:11]
	ds_read_b64_tr_b16 v[20:21], v2 offset:36864
	ds_read_b64_tr_b16 v[22:23], v2 offset:37440
	s_waitcnt lgkmcnt(0)
	v_mfma_f32_16x16x32_bf16 v[12:15], v[20:23], v[84:87], v[12:15]
	s_cbranch_vccnz .Lctx_B_346
	v_mfma_f32_16x16x32_bf16 v[4:7], v[20:23], v[80:83], v[4:7]
.Lctx_B_346:
	ds_read_b64_tr_b16 v[20:21], v2 offset:4608
	ds_read_b64_tr_b16 v[22:23], v2 offset:5184
	s_and_b64 vcc, exec, s[44:45]
	s_waitcnt lgkmcnt(0)
	v_mfma_f32_16x16x32_bf16 v[8:11], v[20:23], v[88:91], v[8:11]
	ds_read_b64_tr_b16 v[20:21], v2 offset:41472
	ds_read_b64_tr_b16 v[22:23], v2 offset:42048
	s_waitcnt lgkmcnt(0)
	v_mfma_f32_16x16x32_bf16 v[12:15], v[20:23], v[92:95], v[12:15]
	s_cbranch_vccnz .Lctx_B_348
	v_mfma_f32_16x16x32_bf16 v[4:7], v[20:23], v[88:91], v[4:7]
.Lctx_B_348:
	ds_read_b64_tr_b16 v[20:21], v2 offset:9216
	ds_read_b64_tr_b16 v[22:23], v2 offset:9792
	s_and_b64 vcc, exec, s[44:45]
	s_waitcnt lgkmcnt(0)
	v_mfma_f32_16x16x32_bf16 v[8:11], v[20:23], v[96:99], v[8:11]
	ds_read_b64_tr_b16 v[20:21], v2 offset:46080
	ds_read_b64_tr_b16 v[22:23], v2 offset:46656
	s_waitcnt lgkmcnt(0)
	v_mfma_f32_16x16x32_bf16 v[12:15], v[20:23], v[100:103], v[12:15]
	s_cbranch_vccnz .Lctx_B_350
	v_mfma_f32_16x16x32_bf16 v[4:7], v[20:23], v[96:99], v[4:7]
.Lctx_B_350:
	ds_read_b64_tr_b16 v[20:21], v2 offset:13824
	ds_read_b64_tr_b16 v[22:23], v2 offset:14400
	s_and_b64 vcc, exec, s[44:45]
	s_waitcnt lgkmcnt(0)
	v_mfma_f32_16x16x32_bf16 v[8:11], v[20:23], v[104:107], v[8:11]
	ds_read_b64_tr_b16 v[20:21], v2 offset:50688
	ds_read_b64_tr_b16 v[22:23], v2 offset:51264
	s_waitcnt lgkmcnt(0)
	v_mfma_f32_16x16x32_bf16 v[12:15], v[20:23], v[108:111], v[12:15]
	s_cbranch_vccnz .Lctx_B_end
	v_mfma_f32_16x16x32_bf16 v[4:7], v[20:23], v[104:107], v[4:7]
.Lctx_B_end:
	s_branch .LBB0_352
.LBB0_352:
	s_and_b32 s6, s16, 7
	v_lshl_add_u32 v2, s6, 5, v26
	v_add_u32_e32 v6, s84, v2
	v_pk_add_f32 v[12:13], v[8:9], v[12:13]
	s_and_b64 vcc, s[4:5], s[40:41]
	v_ashrrev_i32_e32 v7, 31, v6
	v_pk_add_f32 v[10:11], v[10:11], v[14:15]
	v_add_u32_e32 v14, s18, v38
	v_cndmask_b32_e32 v12, v12, v8, vcc
	v_lshlrev_b64 v[6:7], 12, v[6:7]
	s_mov_b32 s6, 0x3b3504f3
	v_lshl_add_u64 v[6:7], s[0:1], 0, v[6:7]
	s_lshl_b32 s10, s17, 1
	v_pk_mul_f32 v[8:9], v[12:13], s[6:7] op_sel_hi:[1,0]
	v_pk_mul_f32 v[10:11], v[10:11], s[6:7] op_sel_hi:[1,0]
	v_ashrrev_i32_e32 v15, 31, v14
	v_lshl_add_u64 v[6:7], v[6:7], 0, s[10:11]
	v_cvt_pk_bf16_f32 v8, v8, v9
	v_cvt_pk_bf16_f32 v9, v10, v11
	v_lshlrev_b64 v[10:11], 1, v[14:15]
	v_lshl_add_u64 v[12:13], v[6:7], 0, v[10:11]
	v_sub_u32_e32 v2, 0, v2
	global_store_dwordx2 v[12:13], v[8:9], off
	v_or_b32_sdwa v12, v2, s84 dst_sel:DWORD dst_unused:UNUSED_PAD src0_sel:BYTE_0 src1_sel:DWORD
	v_ashrrev_i32_e32 v13, 31, v12
	v_lshlrev_b64 v[12:13], 12, v[12:13]
	v_lshl_add_u64 v[12:13], s[0:1], 0, v[12:13]
	v_lshl_add_u64 v[12:13], v[12:13], 0, s[10:11]
	s_xor_b64 s[4:5], vcc, -1
	v_lshl_add_u64 v[10:11], v[12:13], 0, v[10:11]
	s_and_saveexec_b64 s[6:7], s[4:5]
	s_xor_b64 s[4:5], exec, s[6:7]
	s_cbranch_execz .LBB0_354
	global_store_dwordx2 v[10:11], v[8:9], off offset:512
